# rowpass prologues: the four-plane modulation-vector sums are loaded with all loads of a block in flight (one wait per block instead of one per plane); same summation order
# speedup vs baseline: 1.0208x; 1.0208x over previous
.Lcvret_disp:
.Lhk_no:
	s_cmp_eq_u32 s19, 0
	s_cbranch_scc1 .Lp0_entry
	s_cmp_eq_u32 s19, 9
	s_cbranch_scc1 .Lgy_entry
	s_cmp_eq_u32 s19, 8
	s_cbranch_scc1 .Lup_entry
	s_cmp_eq_u32 s19, 6
	s_cbranch_scc1 .Lop_entry
	s_cmp_eq_u32 s19, 2
	s_cbranch_scc1 .Lpj_entry
	s_cmp_lt_i32 s19, 5
	s_cbranch_scc1 .LBB0_46
	s_and_b64 s[20:21], s[22:23], exec
	s_cselect_b32 s18, 0x18000, 0
	s_waitcnt lgkmcnt(0)
	s_add_u32 s66, s24, s18
	s_addc_u32 s80, s25, 0
	s_cmp_gt_i32 s19, 7
	s_cbranch_scc0 .LBB0_47
	s_cmp_gt_i32 s19, 8
	s_cbranch_scc0 .LBB0_48
	s_cmp_gt_i32 s19, 9
	s_cbranch_scc0 .LBB0_64
	s_mov_b64 s[20:21], 0
	s_mov_b64 s[24:25], 0
	s_cmp_eq_u32 s19, 10
	v_writelane_b32 v244, s20, 56
	s_nop 1
	v_writelane_b32 v244, s21, 57
	s_cbranch_scc0 .LBB0_65
	s_load_dwordx2 s[30:31], s[0:1], 0x68
	s_and_b64 vcc, exec, s[6:7]
	s_cbranch_vccz .LBB0_334
	s_lshl_b32 s18, s71, 2
	s_abs_i32 s6, s18
	v_cvt_f32_u32_e32 v0, s6
	s_waitcnt vmcnt(0)
	v_mov_b32_e32 v34, v154
	v_mov_b32_e32 v2, v154
	s_sub_i32 s26, 0, s6
	v_rcp_iflag_f32_e32 v0, v0
	s_nop 0
	v_mul_f32_e32 v0, 0x4f7ffffe, v0
	v_cvt_u32_f32_e32 v0, v0
	v_readfirstlane_b32 s7, v2
	s_ashr_i32 s20, s7, 6
	s_add_i32 s7, s18, 0x3fff
	v_readfirstlane_b32 s27, v0
	s_mul_i32 s26, s26, s27
	s_mul_hi_u32 s26, s27, s26
	s_xor_b32 s21, s7, s18
	s_abs_i32 s7, s7
	s_add_i32 s27, s27, s26
	s_mul_hi_u32 s26, s7, s27
	s_mul_i32 s27, s26, s6
	s_sub_i32 s7, s7, s27
	s_ashr_i32 s21, s21, 31
	s_add_i32 s27, s26, 1
	s_sub_i32 s28, s7, s6
	s_cmp_ge_u32 s7, s6
	s_cselect_b32 s26, s27, s26
	s_cselect_b32 s7, s28, s7
	s_add_i32 s27, s26, 1
	s_cmp_ge_u32 s7, s6
	s_cselect_b32 s6, s27, s26
	s_xor_b32 s6, s6, s21
	s_lshl_b32 s52, s3, 2
	s_sub_i32 s7, s6, s21
	s_add_i32 s6, s20, s52
	s_mul_i32 s6, s6, s7
	s_cmpk_gt_i32 s6, 0x3fff
	s_cbranch_scc1 .LBB0_335
	s_load_dwordx2 s[26:27], s[0:1], 0x110
	s_ashr_i32 s20, s6, 12
	s_mulk_i32 s20, 0x1800
	v_lshlrev_b32_e32 v0, 2, v34
	v_and_b32_e32 v35, 0xfc, v0
	s_waitcnt lgkmcnt(0)
	s_cmp_lg_u64 s[26:27], 0
	s_cselect_b64 s[40:41], -1, 0
	s_ashr_i32 s21, s20, 31
	s_lshl_b64 s[34:35], s[20:21], 2
	s_add_u32 s20, s66, s34
	s_addc_u32 s21, s80, s35
	s_add_u32 s36, s20, 0x5000
	s_addc_u32 s37, s21, 0
	s_and_b64 vcc, exec, s[40:41]
	v_lshlrev_b32_e32 v0, 2, v35
	s_cbranch_vccz .LBB0_30
	global_load_dwordx4 v[188:191], v0, s[36:37]
	s_add_u32 s54, s36, 0x30000
	s_addc_u32 s55, s37, 0
	global_load_dwordx4 v[192:195], v0, s[54:55]
	s_add_u32 s56, s36, 0x60000
	s_addc_u32 s57, s37, 0
	global_load_dwordx4 v[196:199], v0, s[56:57]
	s_add_u32 s62, s36, 0x90000
	s_addc_u32 s63, s37, 0
	global_load_dwordx4 v[200:203], v0, s[62:63]
	global_load_dwordx4 v[2:5], v0, s[30:31]
	s_waitcnt vmcnt(0)
	v_pk_add_f32 v[6:7], v[188:189], v[192:193]
	v_pk_add_f32 v[6:7], v[6:7], v[196:197]
	v_pk_add_f32 v[8:9], v[190:191], v[194:195]
	v_pk_add_f32 v[8:9], v[8:9], v[198:199]
	v_pk_add_f32 v[68:69], v[190:191], v[194:195]
	v_pk_add_f32 v[68:69], v[68:69], v[198:199]
	v_pk_add_f32 v[68:69], v[68:69], v[202:203]
	v_pk_add_f32 v[66:67], v[188:189], v[192:193]
	v_pk_add_f32 v[66:67], v[66:67], v[196:197]
	v_pk_add_f32 v[66:67], v[66:67], v[200:201]
.LBB0_30:
	s_load_dwordx2 s[20:21], s[0:1], 0xc0
	s_load_dwordx2 s[26:27], s[0:1], 0x20
	s_load_dwordx2 s[28:29], s[0:1], 0xb8
	s_waitcnt lgkmcnt(0)
	s_cmp_lg_u64 s[20:21], 0
	s_cselect_b64 s[50:51], -1, 0
	s_add_u32 s28, s28, s34
	s_addc_u32 s29, s29, s35
	s_add_u32 s42, s28, 0x19000
	s_addc_u32 s43, s29, 0
	s_add_u32 s34, s28, 0x18000
	s_addc_u32 s35, s29, 0
	s_add_u32 s48, s26, 0x1000
	s_addc_u32 s49, s27, 0
	s_cmp_eq_u64 s[20:21], 0
	s_cbranch_scc1 .LBB0_32
	global_load_dwordx4 v[188:191], v0, s[42:43]
	s_add_u32 s54, s42, 0x30000
	s_addc_u32 s55, s43, 0
	global_load_dwordx4 v[192:195], v0, s[54:55]
	s_mov_b32 s26, 0x60000
	global_load_dwordx4 v[6:9], v0, s[48:49]
	s_add_u32 s56, s42, 0x60000
	s_addc_u32 s57, s43, 0
	global_load_dwordx4 v[196:199], v0, s[56:57]
	s_add_u32 s62, s42, 0x90000
	s_addc_u32 s63, s43, 0
	global_load_dwordx4 v[200:203], v0, s[62:63]
	global_load_dwordx4 v[204:207], v0, s[34:35]
	s_add_u32 s54, s34, 0x30000
	s_addc_u32 s55, s35, 0
	global_load_dwordx4 v[208:211], v0, s[54:55]
	s_add_u32 s56, s34, 0x60000
	s_addc_u32 s57, s35, 0
	global_load_dwordx4 v[212:215], v0, s[56:57]
	s_mov_b32 s26, 0x90000
	s_add_u32 s62, s34, 0x90000
	s_addc_u32 s63, s35, 0
	global_load_dwordx4 v[216:219], v0, s[62:63]
	s_waitcnt vmcnt(0)
	v_pk_add_f32 v[72:73], v[190:191], v[194:195]
	v_pk_add_f32 v[72:73], v[72:73], v[198:199]
	v_pk_add_f32 v[72:73], v[72:73], v[202:203]
	v_pk_add_f32 v[72:73], v[72:73], 1.0 op_sel_hi:[1,0]
	v_pk_add_f32 v[70:71], v[188:189], v[192:193]
	v_pk_add_f32 v[70:71], v[70:71], v[196:197]
	v_pk_add_f32 v[70:71], v[70:71], v[200:201]
	v_pk_add_f32 v[70:71], v[70:71], 1.0 op_sel_hi:[1,0]
	v_pk_add_f32 v[14:15], v[204:205], v[208:209]
	v_pk_add_f32 v[14:15], v[14:15], v[212:213]
	v_pk_add_f32 v[16:17], v[206:207], v[210:211]
	v_pk_add_f32 v[16:17], v[16:17], v[214:215]
	v_pk_add_f32 v[76:77], v[206:207], v[210:211]
	v_pk_add_f32 v[76:77], v[76:77], v[214:215]
	v_pk_add_f32 v[76:77], v[76:77], v[218:219]
	v_pk_add_f32 v[74:75], v[204:205], v[208:209]
	v_pk_add_f32 v[74:75], v[74:75], v[212:213]
	v_pk_add_f32 v[74:75], v[74:75], v[216:217]
.LBB0_32:
	v_cndmask_b32_e64 v10, 0, 1, s[40:41]
	v_cmp_ne_u32_e64 s[38:39], 1, v10
	s_andn2_b64 vcc, exec, s[40:41]
	s_cbranch_vccnz .LBB0_34
	global_load_dwordx4 v[188:191], v0, s[36:37] offset:1024
	s_add_u32 s54, s36, 0x30000
	s_addc_u32 s55, s37, 0
	global_load_dwordx4 v[192:195], v0, s[54:55] offset:1024
	s_add_u32 s56, s36, 0x60000
	s_addc_u32 s57, s37, 0
	global_load_dwordx4 v[196:199], v0, s[56:57] offset:1024
	s_add_u32 s62, s36, 0x90000
	s_addc_u32 s63, s37, 0
	global_load_dwordx4 v[200:203], v0, s[62:63] offset:1024
	global_load_dwordx4 v[10:13], v0, s[30:31] offset:1024
	s_waitcnt vmcnt(0)
	v_pk_add_f32 v[14:15], v[188:189], v[192:193]
	v_pk_add_f32 v[14:15], v[14:15], v[196:197]
	v_pk_add_f32 v[16:17], v[190:191], v[194:195]
	v_pk_add_f32 v[16:17], v[16:17], v[198:199]
	v_pk_add_f32 v[80:81], v[190:191], v[194:195]
	v_pk_add_f32 v[80:81], v[80:81], v[198:199]
	v_pk_add_f32 v[80:81], v[80:81], v[202:203]
	v_pk_add_f32 v[78:79], v[188:189], v[192:193]
	v_pk_add_f32 v[78:79], v[78:79], v[196:197]
	v_pk_add_f32 v[78:79], v[78:79], v[200:201]
.LBB0_34:
	v_cndmask_b32_e64 v14, 0, 1, s[50:51]
	v_cmp_ne_u32_e64 s[40:41], 1, v14
	s_andn2_b64 vcc, exec, s[50:51]
	s_cbranch_vccnz .LBB0_36
	global_load_dwordx4 v[188:191], v0, s[42:43] offset:1024
	s_add_u32 s54, s42, 0x30000
	s_addc_u32 s55, s43, 0
	global_load_dwordx4 v[192:195], v0, s[54:55] offset:1024
	s_mov_b32 s26, 0x60000
	global_load_dwordx4 v[14:17], v0, s[48:49] offset:1024
	s_add_u32 s56, s42, 0x60000
	s_addc_u32 s57, s43, 0
	global_load_dwordx4 v[196:199], v0, s[56:57] offset:1024
	s_add_u32 s62, s42, 0x90000
	s_addc_u32 s63, s43, 0
	global_load_dwordx4 v[200:203], v0, s[62:63] offset:1024
	global_load_dwordx4 v[204:207], v0, s[34:35] offset:1024
	s_add_u32 s54, s34, 0x30000
	s_addc_u32 s55, s35, 0
	global_load_dwordx4 v[208:211], v0, s[54:55] offset:1024
	s_add_u32 s56, s34, 0x60000
	s_addc_u32 s57, s35, 0
	global_load_dwordx4 v[212:215], v0, s[56:57] offset:1024
	s_mov_b32 s26, 0x90000
	s_add_u32 s62, s34, 0x90000
	s_addc_u32 s63, s35, 0
	global_load_dwordx4 v[216:219], v0, s[62:63] offset:1024
	s_waitcnt vmcnt(0)
	v_pk_add_f32 v[84:85], v[190:191], v[194:195]
	v_pk_add_f32 v[84:85], v[84:85], v[198:199]
	v_pk_add_f32 v[84:85], v[84:85], v[202:203]
	v_pk_add_f32 v[84:85], v[84:85], 1.0 op_sel_hi:[1,0]
	v_pk_add_f32 v[82:83], v[188:189], v[192:193]
	v_pk_add_f32 v[82:83], v[82:83], v[196:197]
	v_pk_add_f32 v[82:83], v[82:83], v[200:201]
	v_pk_add_f32 v[82:83], v[82:83], 1.0 op_sel_hi:[1,0]
	v_pk_add_f32 v[22:23], v[204:205], v[208:209]
	v_pk_add_f32 v[22:23], v[22:23], v[212:213]
	v_pk_add_f32 v[24:25], v[206:207], v[210:211]
	v_pk_add_f32 v[24:25], v[24:25], v[214:215]
	v_pk_add_f32 v[88:89], v[206:207], v[210:211]
	v_pk_add_f32 v[88:89], v[88:89], v[214:215]
	v_pk_add_f32 v[88:89], v[88:89], v[218:219]
	v_pk_add_f32 v[86:87], v[204:205], v[208:209]
	v_pk_add_f32 v[86:87], v[86:87], v[212:213]
	v_pk_add_f32 v[86:87], v[86:87], v[216:217]
.LBB0_36:
	s_and_b64 vcc, exec, s[38:39]
	s_cbranch_vccnz .LBB0_38
	global_load_dwordx4 v[188:191], v0, s[36:37] offset:2048
	s_add_u32 s54, s36, 0x30000
	s_addc_u32 s55, s37, 0
	global_load_dwordx4 v[192:195], v0, s[54:55] offset:2048
	s_add_u32 s56, s36, 0x60000
	s_addc_u32 s57, s37, 0
	global_load_dwordx4 v[196:199], v0, s[56:57] offset:2048
	s_add_u32 s62, s36, 0x90000
	s_addc_u32 s63, s37, 0
	global_load_dwordx4 v[200:203], v0, s[62:63] offset:2048
	global_load_dwordx4 v[18:21], v0, s[30:31] offset:2048
	s_waitcnt vmcnt(0)
	v_pk_add_f32 v[22:23], v[188:189], v[192:193]
	v_pk_add_f32 v[22:23], v[22:23], v[196:197]
	v_pk_add_f32 v[24:25], v[190:191], v[194:195]
	v_pk_add_f32 v[24:25], v[24:25], v[198:199]
	v_pk_add_f32 v[92:93], v[190:191], v[194:195]
	v_pk_add_f32 v[92:93], v[92:93], v[198:199]
	v_pk_add_f32 v[92:93], v[92:93], v[202:203]
	v_pk_add_f32 v[90:91], v[188:189], v[192:193]
	v_pk_add_f32 v[90:91], v[90:91], v[196:197]
	v_pk_add_f32 v[90:91], v[90:91], v[200:201]
.LBB0_38:
	s_and_b64 vcc, exec, s[40:41]
	s_cbranch_vccnz .LBB0_40
	global_load_dwordx4 v[188:191], v0, s[42:43] offset:2048
	s_add_u32 s54, s42, 0x30000
	s_addc_u32 s55, s43, 0
	global_load_dwordx4 v[192:195], v0, s[54:55] offset:2048
	s_mov_b32 s26, 0x60000
	global_load_dwordx4 v[22:25], v0, s[48:49] offset:2048
	s_add_u32 s56, s42, 0x60000
	s_addc_u32 s57, s43, 0
	global_load_dwordx4 v[196:199], v0, s[56:57] offset:2048
	s_add_u32 s62, s42, 0x90000
	s_addc_u32 s63, s43, 0
	global_load_dwordx4 v[200:203], v0, s[62:63] offset:2048
	global_load_dwordx4 v[204:207], v0, s[34:35] offset:2048
	s_add_u32 s54, s34, 0x30000
	s_addc_u32 s55, s35, 0
	global_load_dwordx4 v[208:211], v0, s[54:55] offset:2048
	s_add_u32 s56, s34, 0x60000
	s_addc_u32 s57, s35, 0
	global_load_dwordx4 v[212:215], v0, s[56:57] offset:2048
	s_mov_b32 s26, 0x90000
	s_add_u32 s62, s34, 0x90000
	s_addc_u32 s63, s35, 0
	global_load_dwordx4 v[216:219], v0, s[62:63] offset:2048
	s_waitcnt vmcnt(0)
	v_pk_add_f32 v[96:97], v[190:191], v[194:195]
	v_pk_add_f32 v[96:97], v[96:97], v[198:199]
	v_pk_add_f32 v[96:97], v[96:97], v[202:203]
	v_pk_add_f32 v[96:97], v[96:97], 1.0 op_sel_hi:[1,0]
	v_pk_add_f32 v[94:95], v[188:189], v[192:193]
	v_pk_add_f32 v[94:95], v[94:95], v[196:197]
	v_pk_add_f32 v[94:95], v[94:95], v[200:201]
	v_pk_add_f32 v[94:95], v[94:95], 1.0 op_sel_hi:[1,0]
	v_pk_add_f32 v[30:31], v[204:205], v[208:209]
	v_pk_add_f32 v[30:31], v[30:31], v[212:213]
	v_pk_add_f32 v[32:33], v[206:207], v[210:211]
	v_pk_add_f32 v[32:33], v[32:33], v[214:215]
	v_pk_add_f32 v[108:109], v[206:207], v[210:211]
	v_pk_add_f32 v[108:109], v[108:109], v[214:215]
	v_pk_add_f32 v[108:109], v[108:109], v[218:219]
	v_pk_add_f32 v[106:107], v[204:205], v[208:209]
	v_pk_add_f32 v[106:107], v[106:107], v[212:213]
	v_pk_add_f32 v[106:107], v[106:107], v[216:217]
.LBB0_40:
	s_and_b64 vcc, exec, s[38:39]
	s_cbranch_vccnz .LBB0_42
	global_load_dwordx4 v[188:191], v0, s[36:37] offset:3072
	s_add_u32 s54, s36, 0x30000
	s_addc_u32 s55, s37, 0
	global_load_dwordx4 v[192:195], v0, s[54:55] offset:3072
	s_add_u32 s56, s36, 0x60000
	s_addc_u32 s57, s37, 0
	global_load_dwordx4 v[196:199], v0, s[56:57] offset:3072
	s_add_u32 s62, s36, 0x90000
	s_addc_u32 s63, s37, 0
	global_load_dwordx4 v[200:203], v0, s[62:63] offset:3072
	global_load_dwordx4 v[26:29], v0, s[30:31] offset:3072
	s_waitcnt vmcnt(0)
	v_pk_add_f32 v[30:31], v[188:189], v[192:193]
	v_pk_add_f32 v[30:31], v[30:31], v[196:197]
	v_pk_add_f32 v[32:33], v[190:191], v[194:195]
	v_pk_add_f32 v[32:33], v[32:33], v[198:199]
	v_pk_add_f32 v[112:113], v[190:191], v[194:195]
	v_pk_add_f32 v[112:113], v[112:113], v[198:199]
	v_pk_add_f32 v[112:113], v[112:113], v[202:203]
	v_pk_add_f32 v[110:111], v[188:189], v[192:193]
	v_pk_add_f32 v[110:111], v[110:111], v[196:197]
	v_pk_add_f32 v[110:111], v[110:111], v[200:201]
.LBB0_42:
	s_and_b64 vcc, exec, s[40:41]
	s_cbranch_vccnz .LBB0_44
	global_load_dwordx4 v[188:191], v0, s[42:43] offset:3072
	s_add_u32 s54, s42, 0x30000
	s_addc_u32 s55, s43, 0
	global_load_dwordx4 v[192:195], v0, s[54:55] offset:3072
	s_mov_b32 s26, 0x60000
	global_load_dwordx4 v[30:33], v0, s[48:49] offset:3072
	s_add_u32 s56, s42, 0x60000
	s_addc_u32 s57, s43, 0
	global_load_dwordx4 v[196:199], v0, s[56:57] offset:3072
	s_add_u32 s62, s42, 0x90000
	s_addc_u32 s63, s43, 0
	global_load_dwordx4 v[200:203], v0, s[62:63] offset:3072
	global_load_dwordx4 v[204:207], v0, s[34:35] offset:3072
	s_add_u32 s54, s34, 0x30000
	s_addc_u32 s55, s35, 0
	global_load_dwordx4 v[208:211], v0, s[54:55] offset:3072
	s_add_u32 s56, s34, 0x60000
	s_addc_u32 s57, s35, 0
	global_load_dwordx4 v[212:215], v0, s[56:57] offset:3072
	s_mov_b32 s26, 0x90000
	s_add_u32 s62, s34, 0x90000
	s_addc_u32 s63, s35, 0
	global_load_dwordx4 v[216:219], v0, s[62:63] offset:3072
	s_waitcnt vmcnt(0)
	v_pk_add_f32 v[116:117], v[190:191], v[194:195]
	v_pk_add_f32 v[116:117], v[116:117], v[198:199]
	v_pk_add_f32 v[116:117], v[116:117], v[202:203]
	v_pk_add_f32 v[116:117], v[116:117], 1.0 op_sel_hi:[1,0]
	v_pk_add_f32 v[114:115], v[188:189], v[192:193]
	v_pk_add_f32 v[114:115], v[114:115], v[196:197]
	v_pk_add_f32 v[114:115], v[114:115], v[200:201]
	v_pk_add_f32 v[114:115], v[114:115], 1.0 op_sel_hi:[1,0]
	v_pk_add_f32 v[40:41], v[204:205], v[208:209]
	v_pk_add_f32 v[40:41], v[40:41], v[212:213]
	v_pk_add_f32 v[42:43], v[206:207], v[210:211]
	v_pk_add_f32 v[42:43], v[42:43], v[214:215]
	v_pk_add_f32 v[120:121], v[206:207], v[210:211]
	v_pk_add_f32 v[120:121], v[120:121], v[214:215]
	v_pk_add_f32 v[120:121], v[120:121], v[218:219]
	v_pk_add_f32 v[118:119], v[204:205], v[208:209]
	v_pk_add_f32 v[118:119], v[118:119], v[212:213]
	v_pk_add_f32 v[118:119], v[118:119], v[216:217]

.LBB0_121:
	s_cmp_lt_i32 s19, 6
	s_mov_b64 s[6:7], -1
	s_cbranch_scc1 .LBB0_175
	s_cmp_gt_i32 s19, 6
	s_cbranch_scc0 .LBB0_158
	s_lshl_b32 s6, s71, 2
	s_abs_i32 s7, s6
	v_cvt_f32_u32_e32 v0, s7
	s_sub_i32 s21, 0, s7
	s_add_i32 s20, s6, 0x3fff
	s_xor_b32 s6, s20, s6
	v_rcp_iflag_f32_e32 v0, v0
	s_abs_i32 s20, s20
	s_waitcnt vmcnt(0)
	v_mov_b32_e32 v34, v154
	v_mov_b32_e32 v2, v154
	v_mul_f32_e32 v0, 0x4f7ffffe, v0
	v_cvt_u32_f32_e32 v0, v0
	s_ashr_i32 s6, s6, 31
	v_readfirstlane_b32 s24, v0
	s_mul_i32 s21, s21, s24
	s_mul_hi_u32 s21, s24, s21
	s_add_i32 s24, s24, s21
	s_mul_hi_u32 s21, s20, s24
	s_mul_i32 s24, s21, s7
	v_readfirstlane_b32 s18, v2
	s_sub_i32 s20, s20, s24
	s_ashr_i32 s18, s18, 6
	s_add_i32 s24, s21, 1
	s_sub_i32 s25, s20, s7
	s_cmp_ge_u32 s20, s7
	s_cselect_b32 s21, s24, s21
	s_cselect_b32 s20, s25, s20
	s_add_i32 s24, s21, 1
	s_cmp_ge_u32 s20, s7
	s_cselect_b32 s7, s24, s21
	s_xor_b32 s7, s7, s6
	s_sub_i32 s7, s7, s6
	s_lshl_b32 s6, s3, 2
	s_add_i32 s6, s18, s6
	s_mul_i32 s6, s6, s7
	s_cmpk_gt_i32 s6, 0x3fff
	s_cbranch_scc1 .LBB0_157
	s_load_dwordx2 s[20:21], s[0:1], 0x28
	s_load_dwordx2 s[24:25], s[0:1], 0x110
	s_and_b64 s[26:27], s[22:23], exec
	s_cselect_b32 s18, 0x400, 0
	s_lshl_b32 s18, s18, 2
	s_waitcnt lgkmcnt(0)
	s_add_u32 s28, s20, s18
	s_addc_u32 s29, s21, 0
	s_ashr_i32 s20, s6, 12
	s_cmp_lg_u64 s[24:25], 0
	s_mulk_i32 s20, 0x1800
	s_cselect_b64 s[40:41], -1, 0
	s_ashr_i32 s21, s20, 31
	s_lshl_b64 s[30:31], s[20:21], 2
	s_add_u32 s20, s66, s30
	v_lshlrev_b32_e32 v0, 2, v34
	s_addc_u32 s21, s80, s31
	v_and_b32_e32 v35, 0xfc, v0
	s_add_u32 s34, s20, 0x2000
	s_addc_u32 s35, s21, 0
	s_and_b64 vcc, exec, s[40:41]
	v_lshlrev_b32_e32 v0, 2, v35
	s_cbranch_vccz .LBB0_126
	global_load_dwordx4 v[188:191], v0, s[34:35]
	s_add_u32 s54, s34, 0x30000
	s_addc_u32 s55, s35, 0
	global_load_dwordx4 v[192:195], v0, s[54:55]
	s_add_u32 s56, s34, 0x60000
	s_addc_u32 s57, s35, 0
	global_load_dwordx4 v[196:199], v0, s[56:57]
	s_add_u32 s62, s34, 0x90000
	s_addc_u32 s63, s35, 0
	global_load_dwordx4 v[200:203], v0, s[62:63]
	global_load_dwordx4 v[2:5], v0, s[28:29]
	s_waitcnt vmcnt(0)
	v_pk_add_f32 v[6:7], v[188:189], v[192:193]
	v_pk_add_f32 v[6:7], v[6:7], v[196:197]
	v_pk_add_f32 v[8:9], v[190:191], v[194:195]
	v_pk_add_f32 v[8:9], v[8:9], v[198:199]
	v_pk_add_f32 v[68:69], v[190:191], v[194:195]
	v_pk_add_f32 v[68:69], v[68:69], v[198:199]
	v_pk_add_f32 v[68:69], v[68:69], v[202:203]
	v_pk_add_f32 v[66:67], v[188:189], v[192:193]
	v_pk_add_f32 v[66:67], v[66:67], v[196:197]
	v_pk_add_f32 v[66:67], v[66:67], v[200:201]
.LBB0_126:
	s_load_dwordx2 s[26:27], s[0:1], 0xc0
	s_load_dwordx2 s[20:21], s[0:1], 0x60
	s_waitcnt lgkmcnt(0)
	s_cmp_lg_u64 s[26:27], 0
	s_cselect_b64 s[48:49], -1, 0
	s_add_u32 s30, s66, s30
	s_addc_u32 s31, s80, s31
	s_add_u32 s36, s30, 0x4000
	s_addc_u32 s37, s31, 0
	s_add_u32 s30, s30, 0x3000
	s_addc_u32 s31, s31, 0
	s_add_u32 s42, s20, s18
	s_addc_u32 s43, s21, 0
	s_cmp_eq_u64 s[26:27], 0
	s_cbranch_scc1 .LBB0_128
	global_load_dwordx4 v[188:191], v0, s[36:37]
	s_add_u32 s54, s36, 0x30000
	s_addc_u32 s55, s37, 0
	global_load_dwordx4 v[192:195], v0, s[54:55]
	s_mov_b32 s18, 0x60000
	global_load_dwordx4 v[6:9], v0, s[42:43]
	s_add_u32 s56, s36, 0x60000
	s_addc_u32 s57, s37, 0
	global_load_dwordx4 v[196:199], v0, s[56:57]
	s_add_u32 s62, s36, 0x90000
	s_addc_u32 s63, s37, 0
	global_load_dwordx4 v[200:203], v0, s[62:63]
	global_load_dwordx4 v[204:207], v0, s[30:31]
	s_add_u32 s54, s30, 0x30000
	s_addc_u32 s55, s31, 0
	global_load_dwordx4 v[208:211], v0, s[54:55]
	s_add_u32 s56, s30, 0x60000
	s_addc_u32 s57, s31, 0
	global_load_dwordx4 v[212:215], v0, s[56:57]
	s_mov_b32 s18, 0x90000
	s_add_u32 s62, s30, 0x90000
	s_addc_u32 s63, s31, 0
	global_load_dwordx4 v[216:219], v0, s[62:63]
	s_waitcnt vmcnt(0)
	v_pk_add_f32 v[72:73], v[190:191], v[194:195]
	v_pk_add_f32 v[72:73], v[72:73], v[198:199]
	v_pk_add_f32 v[72:73], v[72:73], v[202:203]
	v_pk_add_f32 v[72:73], v[72:73], 1.0 op_sel_hi:[1,0]
	v_pk_add_f32 v[70:71], v[188:189], v[192:193]
	v_pk_add_f32 v[70:71], v[70:71], v[196:197]
	v_pk_add_f32 v[70:71], v[70:71], v[200:201]
	v_pk_add_f32 v[70:71], v[70:71], 1.0 op_sel_hi:[1,0]
	v_pk_add_f32 v[14:15], v[204:205], v[208:209]
	v_pk_add_f32 v[14:15], v[14:15], v[212:213]
	v_pk_add_f32 v[16:17], v[206:207], v[210:211]
	v_pk_add_f32 v[16:17], v[16:17], v[214:215]
	v_pk_add_f32 v[76:77], v[206:207], v[210:211]
	v_pk_add_f32 v[76:77], v[76:77], v[214:215]
	v_pk_add_f32 v[76:77], v[76:77], v[218:219]
	v_pk_add_f32 v[74:75], v[204:205], v[208:209]
	v_pk_add_f32 v[74:75], v[74:75], v[212:213]
	v_pk_add_f32 v[74:75], v[74:75], v[216:217]
.LBB0_128:
	v_cndmask_b32_e64 v10, 0, 1, s[40:41]
	v_cmp_ne_u32_e64 s[38:39], 1, v10
	s_andn2_b64 vcc, exec, s[40:41]
	s_cbranch_vccnz .LBB0_130
	global_load_dwordx4 v[188:191], v0, s[34:35] offset:1024
	s_add_u32 s54, s34, 0x30000
	s_addc_u32 s55, s35, 0
	global_load_dwordx4 v[192:195], v0, s[54:55] offset:1024
	s_add_u32 s56, s34, 0x60000
	s_addc_u32 s57, s35, 0
	global_load_dwordx4 v[196:199], v0, s[56:57] offset:1024
	s_add_u32 s62, s34, 0x90000
	s_addc_u32 s63, s35, 0
	global_load_dwordx4 v[200:203], v0, s[62:63] offset:1024
	global_load_dwordx4 v[10:13], v0, s[28:29] offset:1024
	s_waitcnt vmcnt(0)
	v_pk_add_f32 v[14:15], v[188:189], v[192:193]
	v_pk_add_f32 v[14:15], v[14:15], v[196:197]
	v_pk_add_f32 v[16:17], v[190:191], v[194:195]
	v_pk_add_f32 v[16:17], v[16:17], v[198:199]
	v_pk_add_f32 v[80:81], v[190:191], v[194:195]
	v_pk_add_f32 v[80:81], v[80:81], v[198:199]
	v_pk_add_f32 v[80:81], v[80:81], v[202:203]
	v_pk_add_f32 v[78:79], v[188:189], v[192:193]
	v_pk_add_f32 v[78:79], v[78:79], v[196:197]
	v_pk_add_f32 v[78:79], v[78:79], v[200:201]
.LBB0_130:
	v_cndmask_b32_e64 v14, 0, 1, s[48:49]
	v_cmp_ne_u32_e64 s[40:41], 1, v14
	s_andn2_b64 vcc, exec, s[48:49]
	s_cbranch_vccnz .LBB0_132
	global_load_dwordx4 v[188:191], v0, s[36:37] offset:1024
	s_add_u32 s54, s36, 0x30000
	s_addc_u32 s55, s37, 0
	global_load_dwordx4 v[192:195], v0, s[54:55] offset:1024
	s_mov_b32 s18, 0x60000
	global_load_dwordx4 v[14:17], v0, s[42:43] offset:1024
	s_add_u32 s56, s36, 0x60000
	s_addc_u32 s57, s37, 0
	global_load_dwordx4 v[196:199], v0, s[56:57] offset:1024
	s_add_u32 s62, s36, 0x90000
	s_addc_u32 s63, s37, 0
	global_load_dwordx4 v[200:203], v0, s[62:63] offset:1024
	global_load_dwordx4 v[204:207], v0, s[30:31] offset:1024
	s_add_u32 s54, s30, 0x30000
	s_addc_u32 s55, s31, 0
	global_load_dwordx4 v[208:211], v0, s[54:55] offset:1024
	s_add_u32 s56, s30, 0x60000
	s_addc_u32 s57, s31, 0
	global_load_dwordx4 v[212:215], v0, s[56:57] offset:1024
	s_mov_b32 s18, 0x90000
	s_add_u32 s62, s30, 0x90000
	s_addc_u32 s63, s31, 0
	global_load_dwordx4 v[216:219], v0, s[62:63] offset:1024
	s_waitcnt vmcnt(0)
	v_pk_add_f32 v[84:85], v[190:191], v[194:195]
	v_pk_add_f32 v[84:85], v[84:85], v[198:199]
	v_pk_add_f32 v[84:85], v[84:85], v[202:203]
	v_pk_add_f32 v[84:85], v[84:85], 1.0 op_sel_hi:[1,0]
	v_pk_add_f32 v[82:83], v[188:189], v[192:193]
	v_pk_add_f32 v[82:83], v[82:83], v[196:197]
	v_pk_add_f32 v[82:83], v[82:83], v[200:201]
	v_pk_add_f32 v[82:83], v[82:83], 1.0 op_sel_hi:[1,0]
	v_pk_add_f32 v[22:23], v[204:205], v[208:209]
	v_pk_add_f32 v[22:23], v[22:23], v[212:213]
	v_pk_add_f32 v[24:25], v[206:207], v[210:211]
	v_pk_add_f32 v[24:25], v[24:25], v[214:215]
	v_pk_add_f32 v[88:89], v[206:207], v[210:211]
	v_pk_add_f32 v[88:89], v[88:89], v[214:215]
	v_pk_add_f32 v[88:89], v[88:89], v[218:219]
	v_pk_add_f32 v[86:87], v[204:205], v[208:209]
	v_pk_add_f32 v[86:87], v[86:87], v[212:213]
	v_pk_add_f32 v[86:87], v[86:87], v[216:217]
.LBB0_132:
	s_and_b64 vcc, exec, s[38:39]
	s_cbranch_vccnz .LBB0_134
	global_load_dwordx4 v[188:191], v0, s[34:35] offset:2048
	s_add_u32 s54, s34, 0x30000
	s_addc_u32 s55, s35, 0
	global_load_dwordx4 v[192:195], v0, s[54:55] offset:2048
	s_add_u32 s56, s34, 0x60000
	s_addc_u32 s57, s35, 0
	global_load_dwordx4 v[196:199], v0, s[56:57] offset:2048
	s_add_u32 s62, s34, 0x90000
	s_addc_u32 s63, s35, 0
	global_load_dwordx4 v[200:203], v0, s[62:63] offset:2048
	global_load_dwordx4 v[18:21], v0, s[28:29] offset:2048
	s_waitcnt vmcnt(0)
	v_pk_add_f32 v[22:23], v[188:189], v[192:193]
	v_pk_add_f32 v[22:23], v[22:23], v[196:197]
	v_pk_add_f32 v[24:25], v[190:191], v[194:195]
	v_pk_add_f32 v[24:25], v[24:25], v[198:199]
	v_pk_add_f32 v[92:93], v[190:191], v[194:195]
	v_pk_add_f32 v[92:93], v[92:93], v[198:199]
	v_pk_add_f32 v[92:93], v[92:93], v[202:203]
	v_pk_add_f32 v[90:91], v[188:189], v[192:193]
	v_pk_add_f32 v[90:91], v[90:91], v[196:197]
	v_pk_add_f32 v[90:91], v[90:91], v[200:201]
.LBB0_134:
	s_and_b64 vcc, exec, s[40:41]
	s_cbranch_vccnz .LBB0_136
	global_load_dwordx4 v[188:191], v0, s[36:37] offset:2048
	s_add_u32 s54, s36, 0x30000
	s_addc_u32 s55, s37, 0
	global_load_dwordx4 v[192:195], v0, s[54:55] offset:2048
	s_mov_b32 s18, 0x60000
	global_load_dwordx4 v[22:25], v0, s[42:43] offset:2048
	s_add_u32 s56, s36, 0x60000
	s_addc_u32 s57, s37, 0
	global_load_dwordx4 v[196:199], v0, s[56:57] offset:2048
	s_add_u32 s62, s36, 0x90000
	s_addc_u32 s63, s37, 0
	global_load_dwordx4 v[200:203], v0, s[62:63] offset:2048
	global_load_dwordx4 v[204:207], v0, s[30:31] offset:2048
	s_add_u32 s54, s30, 0x30000
	s_addc_u32 s55, s31, 0
	global_load_dwordx4 v[208:211], v0, s[54:55] offset:2048
	s_add_u32 s56, s30, 0x60000
	s_addc_u32 s57, s31, 0
	global_load_dwordx4 v[212:215], v0, s[56:57] offset:2048
	s_mov_b32 s18, 0x90000
	s_add_u32 s62, s30, 0x90000
	s_addc_u32 s63, s31, 0
	global_load_dwordx4 v[216:219], v0, s[62:63] offset:2048
	s_waitcnt vmcnt(0)
	v_pk_add_f32 v[96:97], v[190:191], v[194:195]
	v_pk_add_f32 v[96:97], v[96:97], v[198:199]
	v_pk_add_f32 v[96:97], v[96:97], v[202:203]
	v_pk_add_f32 v[96:97], v[96:97], 1.0 op_sel_hi:[1,0]
	v_pk_add_f32 v[94:95], v[188:189], v[192:193]
	v_pk_add_f32 v[94:95], v[94:95], v[196:197]
	v_pk_add_f32 v[94:95], v[94:95], v[200:201]
	v_pk_add_f32 v[94:95], v[94:95], 1.0 op_sel_hi:[1,0]
	v_pk_add_f32 v[30:31], v[204:205], v[208:209]
	v_pk_add_f32 v[30:31], v[30:31], v[212:213]
	v_pk_add_f32 v[32:33], v[206:207], v[210:211]
	v_pk_add_f32 v[32:33], v[32:33], v[214:215]
	v_pk_add_f32 v[108:109], v[206:207], v[210:211]
	v_pk_add_f32 v[108:109], v[108:109], v[214:215]
	v_pk_add_f32 v[108:109], v[108:109], v[218:219]
	v_pk_add_f32 v[106:107], v[204:205], v[208:209]
	v_pk_add_f32 v[106:107], v[106:107], v[212:213]
	v_pk_add_f32 v[106:107], v[106:107], v[216:217]
.LBB0_136:
	s_and_b64 vcc, exec, s[38:39]
	s_cbranch_vccnz .LBB0_138
	global_load_dwordx4 v[188:191], v0, s[34:35] offset:3072
	s_add_u32 s54, s34, 0x30000
	s_addc_u32 s55, s35, 0
	global_load_dwordx4 v[192:195], v0, s[54:55] offset:3072
	s_add_u32 s56, s34, 0x60000
	s_addc_u32 s57, s35, 0
	global_load_dwordx4 v[196:199], v0, s[56:57] offset:3072
	s_add_u32 s62, s34, 0x90000
	s_addc_u32 s63, s35, 0
	global_load_dwordx4 v[200:203], v0, s[62:63] offset:3072
	global_load_dwordx4 v[26:29], v0, s[28:29] offset:3072
	s_waitcnt vmcnt(0)
	v_pk_add_f32 v[30:31], v[188:189], v[192:193]
	v_pk_add_f32 v[30:31], v[30:31], v[196:197]
	v_pk_add_f32 v[32:33], v[190:191], v[194:195]
	v_pk_add_f32 v[32:33], v[32:33], v[198:199]
	v_pk_add_f32 v[112:113], v[190:191], v[194:195]
	v_pk_add_f32 v[112:113], v[112:113], v[198:199]
	v_pk_add_f32 v[112:113], v[112:113], v[202:203]
	v_pk_add_f32 v[110:111], v[188:189], v[192:193]
	v_pk_add_f32 v[110:111], v[110:111], v[196:197]
	v_pk_add_f32 v[110:111], v[110:111], v[200:201]
.LBB0_138:
	s_and_b64 vcc, exec, s[40:41]
	s_cbranch_vccnz .LBB0_140
	global_load_dwordx4 v[188:191], v0, s[36:37] offset:3072
	s_add_u32 s54, s36, 0x30000
	s_addc_u32 s55, s37, 0
	global_load_dwordx4 v[192:195], v0, s[54:55] offset:3072
	s_mov_b32 s18, 0x60000
	global_load_dwordx4 v[30:33], v0, s[42:43] offset:3072
	s_add_u32 s56, s36, 0x60000
	s_addc_u32 s57, s37, 0
	global_load_dwordx4 v[196:199], v0, s[56:57] offset:3072
	s_add_u32 s62, s36, 0x90000
	s_addc_u32 s63, s37, 0
	global_load_dwordx4 v[200:203], v0, s[62:63] offset:3072
	global_load_dwordx4 v[204:207], v0, s[30:31] offset:3072
	s_add_u32 s54, s30, 0x30000
	s_addc_u32 s55, s31, 0
	global_load_dwordx4 v[208:211], v0, s[54:55] offset:3072
	s_add_u32 s56, s30, 0x60000
	s_addc_u32 s57, s31, 0
	global_load_dwordx4 v[212:215], v0, s[56:57] offset:3072
	s_mov_b32 s18, 0x90000
	s_add_u32 s62, s30, 0x90000
	s_addc_u32 s63, s31, 0
	global_load_dwordx4 v[216:219], v0, s[62:63] offset:3072
	s_waitcnt vmcnt(0)
	v_pk_add_f32 v[116:117], v[190:191], v[194:195]
	v_pk_add_f32 v[116:117], v[116:117], v[198:199]
	v_pk_add_f32 v[116:117], v[116:117], v[202:203]
	v_pk_add_f32 v[116:117], v[116:117], 1.0 op_sel_hi:[1,0]
	v_pk_add_f32 v[114:115], v[188:189], v[192:193]
	v_pk_add_f32 v[114:115], v[114:115], v[196:197]
	v_pk_add_f32 v[114:115], v[114:115], v[200:201]
	v_pk_add_f32 v[114:115], v[114:115], 1.0 op_sel_hi:[1,0]
	v_pk_add_f32 v[40:41], v[204:205], v[208:209]
	v_pk_add_f32 v[40:41], v[40:41], v[212:213]
	v_pk_add_f32 v[42:43], v[206:207], v[210:211]
	v_pk_add_f32 v[42:43], v[42:43], v[214:215]
	v_pk_add_f32 v[120:121], v[206:207], v[210:211]
	v_pk_add_f32 v[120:121], v[120:121], v[214:215]
	v_pk_add_f32 v[120:121], v[120:121], v[218:219]
	v_pk_add_f32 v[118:119], v[204:205], v[208:209]
	v_pk_add_f32 v[118:119], v[118:119], v[212:213]
	v_pk_add_f32 v[118:119], v[118:119], v[216:217]

.LBB0_304:
	s_andn2_b64 vcc, exec, s[6:7]
	s_cbranch_vccnz .LBB0_397
	s_cmp_gt_i32 s19, 0
	s_mov_b64 s[6:7], -1
	s_cbranch_scc0 .LBB0_325
	s_lshl_b32 s6, s71, 2
	s_abs_i32 s7, s6
	v_cvt_f32_u32_e32 v0, s7
	s_sub_i32 s21, 0, s7
	s_add_i32 s20, s6, 0x3fff
	s_xor_b32 s6, s20, s6
	v_rcp_iflag_f32_e32 v0, v0
	s_abs_i32 s20, s20
	s_waitcnt vmcnt(0)
	v_mov_b32_e32 v18, v154
	v_mov_b32_e32 v2, v154
	v_mul_f32_e32 v0, 0x4f7ffffe, v0
	v_cvt_u32_f32_e32 v0, v0
	s_ashr_i32 s6, s6, 31
	v_readfirstlane_b32 s22, v0
	s_mul_i32 s21, s21, s22
	s_mul_hi_u32 s21, s22, s21
	s_add_i32 s22, s22, s21
	s_mul_hi_u32 s21, s20, s22
	s_mul_i32 s22, s21, s7
	v_readfirstlane_b32 s18, v2
	s_sub_i32 s20, s20, s22
	s_ashr_i32 s18, s18, 6
	s_add_i32 s22, s21, 1
	s_sub_i32 s23, s20, s7
	s_cmp_ge_u32 s20, s7
	s_cselect_b32 s21, s22, s21
	s_cselect_b32 s20, s23, s20
	s_add_i32 s22, s21, 1
	s_cmp_ge_u32 s20, s7
	s_cselect_b32 s7, s22, s21
	s_xor_b32 s7, s7, s6
	s_sub_i32 s7, s7, s6
	s_lshl_b32 s6, s3, 2
	s_add_i32 s6, s18, s6
	s_mul_i32 s6, s6, s7
	s_cmpk_gt_i32 s6, 0x3fff
	s_cbranch_scc1 .LBB0_324
	s_waitcnt lgkmcnt(0)
	s_load_dwordx2 s[24:25], s[0:1], 0xc0
	s_load_dwordx2 s[28:29], s[0:1], 0x20
	s_ashr_i32 s18, s6, 12
	s_load_dwordx2 s[26:27], s[0:1], 0xb8
	s_mul_i32 s20, s18, 0x1800
	s_waitcnt lgkmcnt(0)
	s_cmp_eq_u64 s[24:25], 0
	s_cselect_b64 s[22:23], -1, 0
	s_cmp_lg_u64 s[24:25], 0
	s_cselect_b64 s[34:35], -1, 0
	s_ashr_i32 s21, s20, 31
	s_lshl_b64 s[20:21], s[20:21], 2
	s_add_u32 s26, s26, s20
	v_lshlrev_b32_e32 v0, 2, v18
	s_addc_u32 s27, s27, s21
	v_and_b32_e32 v0, 0xfc, v0
	s_add_u32 s30, s26, 0x1000
	s_addc_u32 s31, s27, 0
	s_and_b64 vcc, exec, s[34:35]
	v_lshlrev_b32_e32 v0, 2, v0
	s_cbranch_vccz .LBB0_309
	global_load_dwordx4 v[188:191], v0, s[30:31]
	s_add_u32 s54, s30, 0x30000
	s_addc_u32 s55, s31, 0
	global_load_dwordx4 v[192:195], v0, s[54:55]
	s_mov_b32 s18, 0x60000
	global_load_dwordx4 v[2:5], v0, s[28:29]
	s_add_u32 s56, s30, 0x60000
	s_addc_u32 s57, s31, 0
	global_load_dwordx4 v[196:199], v0, s[56:57]
	s_add_u32 s62, s30, 0x90000
	s_addc_u32 s63, s31, 0
	global_load_dwordx4 v[200:203], v0, s[62:63]
	global_load_dwordx4 v[204:207], v0, s[26:27]
	s_add_u32 s54, s26, 0x30000
	s_addc_u32 s55, s27, 0
	global_load_dwordx4 v[208:211], v0, s[54:55]
	s_add_u32 s56, s26, 0x60000
	s_addc_u32 s57, s27, 0
	global_load_dwordx4 v[212:215], v0, s[56:57]
	s_mov_b32 s18, 0x90000
	s_add_u32 s62, s26, 0x90000
	s_addc_u32 s63, s27, 0
	global_load_dwordx4 v[216:219], v0, s[62:63]
	s_waitcnt vmcnt(0)
	v_pk_add_f32 v[52:53], v[190:191], v[194:195]
	v_pk_add_f32 v[52:53], v[52:53], v[198:199]
	v_pk_add_f32 v[52:53], v[52:53], v[202:203]
	v_pk_add_f32 v[52:53], v[52:53], 1.0 op_sel_hi:[1,0]
	v_pk_add_f32 v[50:51], v[188:189], v[192:193]
	v_pk_add_f32 v[50:51], v[50:51], v[196:197]
	v_pk_add_f32 v[50:51], v[50:51], v[200:201]
	v_pk_add_f32 v[50:51], v[50:51], 1.0 op_sel_hi:[1,0]
	v_pk_add_f32 v[10:11], v[204:205], v[208:209]
	v_pk_add_f32 v[10:11], v[10:11], v[212:213]
	v_pk_add_f32 v[12:13], v[206:207], v[210:211]
	v_pk_add_f32 v[12:13], v[12:13], v[214:215]
	v_pk_add_f32 v[56:57], v[206:207], v[210:211]
	v_pk_add_f32 v[56:57], v[56:57], v[214:215]
	v_pk_add_f32 v[56:57], v[56:57], v[218:219]
	v_pk_add_f32 v[54:55], v[204:205], v[208:209]
	v_pk_add_f32 v[54:55], v[54:55], v[212:213]
	v_pk_add_f32 v[54:55], v[54:55], v[216:217]
.LBB0_309:
	v_cndmask_b32_e64 v6, 0, 1, s[34:35]
	v_cmp_ne_u32_e64 s[38:39], 1, v6
	s_andn2_b64 vcc, exec, s[34:35]
	s_cbranch_vccnz .LBB0_311
	global_load_dwordx4 v[188:191], v0, s[30:31] offset:1024
	s_add_u32 s54, s30, 0x30000
	s_addc_u32 s55, s31, 0
	global_load_dwordx4 v[192:195], v0, s[54:55] offset:1024
	s_mov_b32 s18, 0x60000
	global_load_dwordx4 v[6:9], v0, s[28:29] offset:1024
	s_add_u32 s56, s30, 0x60000
	s_addc_u32 s57, s31, 0
	global_load_dwordx4 v[196:199], v0, s[56:57] offset:1024
	s_add_u32 s62, s30, 0x90000
	s_addc_u32 s63, s31, 0
	global_load_dwordx4 v[200:203], v0, s[62:63] offset:1024
	global_load_dwordx4 v[204:207], v0, s[26:27] offset:1024
	s_add_u32 s54, s26, 0x30000
	s_addc_u32 s55, s27, 0
	global_load_dwordx4 v[208:211], v0, s[54:55] offset:1024
	s_add_u32 s56, s26, 0x60000
	s_addc_u32 s57, s27, 0
	global_load_dwordx4 v[212:215], v0, s[56:57] offset:1024
	s_mov_b32 s18, 0x90000
	s_add_u32 s62, s26, 0x90000
	s_addc_u32 s63, s27, 0
	global_load_dwordx4 v[216:219], v0, s[62:63] offset:1024
	s_waitcnt vmcnt(0)
	v_pk_add_f32 v[60:61], v[190:191], v[194:195]
	v_pk_add_f32 v[60:61], v[60:61], v[198:199]
	v_pk_add_f32 v[60:61], v[60:61], v[202:203]
	v_pk_add_f32 v[60:61], v[60:61], 1.0 op_sel_hi:[1,0]
	v_pk_add_f32 v[58:59], v[188:189], v[192:193]
	v_pk_add_f32 v[58:59], v[58:59], v[196:197]
	v_pk_add_f32 v[58:59], v[58:59], v[200:201]
	v_pk_add_f32 v[58:59], v[58:59], 1.0 op_sel_hi:[1,0]
	v_pk_add_f32 v[14:15], v[204:205], v[208:209]
	v_pk_add_f32 v[14:15], v[14:15], v[212:213]
	v_pk_add_f32 v[16:17], v[206:207], v[210:211]
	v_pk_add_f32 v[16:17], v[16:17], v[214:215]
	v_pk_add_f32 v[64:65], v[206:207], v[210:211]
	v_pk_add_f32 v[64:65], v[64:65], v[214:215]
	v_pk_add_f32 v[64:65], v[64:65], v[218:219]
	v_pk_add_f32 v[62:63], v[204:205], v[208:209]
	v_pk_add_f32 v[62:63], v[62:63], v[212:213]
	v_pk_add_f32 v[62:63], v[62:63], v[216:217]
.LBB0_311:
	s_and_b64 vcc, exec, s[38:39]
	s_cbranch_vccnz .LBB0_313
	global_load_dwordx4 v[188:191], v0, s[30:31] offset:2048
	s_add_u32 s54, s30, 0x30000
	s_addc_u32 s55, s31, 0
	global_load_dwordx4 v[192:195], v0, s[54:55] offset:2048
	s_mov_b32 s18, 0x60000
	global_load_dwordx4 v[10:13], v0, s[28:29] offset:2048
	s_add_u32 s56, s30, 0x60000
	s_addc_u32 s57, s31, 0
	global_load_dwordx4 v[196:199], v0, s[56:57] offset:2048
	s_add_u32 s62, s30, 0x90000
	s_addc_u32 s63, s31, 0
	global_load_dwordx4 v[200:203], v0, s[62:63] offset:2048
	global_load_dwordx4 v[204:207], v0, s[26:27] offset:2048
	s_add_u32 s54, s26, 0x30000
	s_addc_u32 s55, s27, 0
	global_load_dwordx4 v[208:211], v0, s[54:55] offset:2048
	s_add_u32 s56, s26, 0x60000
	s_addc_u32 s57, s27, 0
	global_load_dwordx4 v[212:215], v0, s[56:57] offset:2048
	s_mov_b32 s18, 0x90000
	s_add_u32 s62, s26, 0x90000
	s_addc_u32 s63, s27, 0
	global_load_dwordx4 v[216:219], v0, s[62:63] offset:2048
	s_waitcnt vmcnt(0)
	v_pk_add_f32 v[68:69], v[190:191], v[194:195]
	v_pk_add_f32 v[68:69], v[68:69], v[198:199]
	v_pk_add_f32 v[68:69], v[68:69], v[202:203]
	v_pk_add_f32 v[68:69], v[68:69], 1.0 op_sel_hi:[1,0]
	v_pk_add_f32 v[66:67], v[188:189], v[192:193]
	v_pk_add_f32 v[66:67], v[66:67], v[196:197]
	v_pk_add_f32 v[66:67], v[66:67], v[200:201]
	v_pk_add_f32 v[66:67], v[66:67], 1.0 op_sel_hi:[1,0]
	v_pk_add_f32 v[20:21], v[204:205], v[208:209]
	v_pk_add_f32 v[20:21], v[20:21], v[212:213]
	v_pk_add_f32 v[22:23], v[206:207], v[210:211]
	v_pk_add_f32 v[22:23], v[22:23], v[214:215]
	v_pk_add_f32 v[72:73], v[206:207], v[210:211]
	v_pk_add_f32 v[72:73], v[72:73], v[214:215]
	v_pk_add_f32 v[72:73], v[72:73], v[218:219]
	v_pk_add_f32 v[70:71], v[204:205], v[208:209]
	v_pk_add_f32 v[70:71], v[70:71], v[212:213]
	v_pk_add_f32 v[70:71], v[70:71], v[216:217]
.LBB0_313:
	s_and_b64 vcc, exec, s[38:39]
	s_cbranch_vccnz .LBB0_315
	global_load_dwordx4 v[188:191], v0, s[30:31] offset:3072
	s_add_u32 s54, s30, 0x30000
	s_addc_u32 s55, s31, 0
	global_load_dwordx4 v[192:195], v0, s[54:55] offset:3072
	s_mov_b32 s18, 0x60000
	global_load_dwordx4 v[14:17], v0, s[28:29] offset:3072
	s_add_u32 s56, s30, 0x60000
	s_addc_u32 s57, s31, 0
	global_load_dwordx4 v[196:199], v0, s[56:57] offset:3072
	s_add_u32 s62, s30, 0x90000
	s_addc_u32 s63, s31, 0
	global_load_dwordx4 v[200:203], v0, s[62:63] offset:3072
	global_load_dwordx4 v[204:207], v0, s[26:27] offset:3072
	s_add_u32 s54, s26, 0x30000
	s_addc_u32 s55, s27, 0
	global_load_dwordx4 v[208:211], v0, s[54:55] offset:3072
	s_add_u32 s56, s26, 0x60000
	s_addc_u32 s57, s27, 0
	global_load_dwordx4 v[212:215], v0, s[56:57] offset:3072
	s_mov_b32 s18, 0x90000
	s_add_u32 s62, s26, 0x90000
	s_addc_u32 s63, s27, 0
	global_load_dwordx4 v[216:219], v0, s[62:63] offset:3072
	s_add_i32 s7, s6, s7
	s_min_i32 s18, s7, 0x4000
	s_cmp_lt_i32 s6, s18
	s_waitcnt vmcnt(0)
	v_pk_add_f32 v[76:77], v[190:191], v[194:195]
	v_pk_add_f32 v[76:77], v[76:77], v[198:199]
	v_pk_add_f32 v[76:77], v[76:77], v[202:203]
	v_pk_add_f32 v[76:77], v[76:77], 1.0 op_sel_hi:[1,0]
	v_pk_add_f32 v[74:75], v[188:189], v[192:193]
	v_pk_add_f32 v[74:75], v[74:75], v[196:197]
	v_pk_add_f32 v[74:75], v[74:75], v[200:201]
	v_pk_add_f32 v[74:75], v[74:75], 1.0 op_sel_hi:[1,0]
	v_pk_add_f32 v[24:25], v[204:205], v[208:209]
	v_pk_add_f32 v[24:25], v[24:25], v[212:213]
	v_pk_add_f32 v[26:27], v[206:207], v[210:211]
	v_pk_add_f32 v[26:27], v[26:27], v[214:215]
	v_pk_add_f32 v[80:81], v[206:207], v[210:211]
	v_pk_add_f32 v[80:81], v[80:81], v[214:215]
	v_pk_add_f32 v[80:81], v[80:81], v[218:219]
	v_pk_add_f32 v[78:79], v[204:205], v[208:209]
	v_pk_add_f32 v[78:79], v[78:79], v[212:213]
	v_pk_add_f32 v[78:79], v[78:79], v[216:217]
	s_cbranch_scc0 .LBB0_324
	s_branch .LBB0_316

.LBB0_520:
	s_and_b64 vcc, exec, s[6:7]
	s_cbranch_vccz .LBB0_65
	s_lshl_b32 s6, s71, 2
	s_abs_i32 s7, s6
	v_cvt_f32_u32_e32 v0, s7
	s_sub_i32 s21, 0, s7
	s_add_i32 s20, s6, 0x3fff
	s_xor_b32 s6, s20, s6
	v_rcp_iflag_f32_e32 v0, v0
	s_abs_i32 s20, s20
	s_waitcnt vmcnt(0)
	v_mov_b32_e32 v18, v154
	s_waitcnt vmcnt(3)
	v_mov_b32_e32 v2, v154
	v_mul_f32_e32 v0, 0x4f7ffffe, v0
	v_cvt_u32_f32_e32 v0, v0
	s_ashr_i32 s6, s6, 31
	v_readfirstlane_b32 s26, v0
	s_mul_i32 s21, s21, s26
	s_mul_hi_u32 s21, s26, s21
	s_add_i32 s26, s26, s21
	s_mul_hi_u32 s21, s20, s26
	s_mul_i32 s26, s21, s7
	v_readfirstlane_b32 s18, v2
	s_sub_i32 s20, s20, s26
	s_ashr_i32 s18, s18, 6
	s_add_i32 s26, s21, 1
	s_sub_i32 s27, s20, s7
	s_cmp_ge_u32 s20, s7
	s_cselect_b32 s21, s26, s21
	s_cselect_b32 s20, s27, s20
	s_add_i32 s26, s21, 1
	s_cmp_ge_u32 s20, s7
	s_cselect_b32 s7, s26, s21
	s_xor_b32 s7, s7, s6
	s_sub_i32 s7, s7, s6
	s_lshl_b32 s6, s3, 2
	s_add_i32 s6, s18, s6
	s_mul_i32 s6, s6, s7
	s_cmpk_gt_i32 s6, 0x3fff
	s_cbranch_scc1 .LBB0_65
	s_load_dwordx2 s[20:21], s[0:1], 0x110
	s_waitcnt lgkmcnt(0)
	s_add_u32 s30, s30, 0x1000
	s_addc_u32 s31, s31, 0
	s_ashr_i32 s18, s6, 12
	v_lshlrev_b32_e32 v0, 2, v18
	s_cmp_lg_u64 s[20:21], 0
	s_mul_i32 s20, s18, 0x1800
	s_cselect_b64 s[36:37], -1, 0
	s_ashr_i32 s21, s20, 31
	s_lshl_b64 s[20:21], s[20:21], 2
	s_add_u32 s18, s66, s20
	s_addc_u32 s20, s80, s21
	v_and_b32_e32 v19, 0xfc, v0
	s_add_u32 s34, s18, 0x5000
	s_addc_u32 s35, s20, 0
	s_and_b64 vcc, exec, s[36:37]
	v_lshlrev_b32_e32 v0, 2, v19
	s_cbranch_vccz .LBB0_524
	global_load_dwordx4 v[188:191], v0, s[34:35]
	s_add_u32 s54, s34, 0x30000
	s_addc_u32 s55, s35, 0
	global_load_dwordx4 v[192:195], v0, s[54:55]
	s_add_u32 s56, s34, 0x60000
	s_addc_u32 s57, s35, 0
	global_load_dwordx4 v[196:199], v0, s[56:57]
	s_add_u32 s62, s34, 0x90000
	s_addc_u32 s63, s35, 0
	global_load_dwordx4 v[200:203], v0, s[62:63]
	global_load_dwordx4 v[2:5], v0, s[30:31]
	s_waitcnt vmcnt(0)
	v_pk_add_f32 v[6:7], v[188:189], v[192:193]
	v_pk_add_f32 v[6:7], v[6:7], v[196:197]
	v_pk_add_f32 v[8:9], v[190:191], v[194:195]
	v_pk_add_f32 v[8:9], v[8:9], v[198:199]
	v_pk_add_f32 v[52:53], v[190:191], v[194:195]
	v_pk_add_f32 v[52:53], v[52:53], v[198:199]
	v_pk_add_f32 v[52:53], v[52:53], v[202:203]
	v_pk_add_f32 v[50:51], v[188:189], v[192:193]
	v_pk_add_f32 v[50:51], v[50:51], v[196:197]
	v_pk_add_f32 v[50:51], v[50:51], v[200:201]
.LBB0_524:
	s_waitcnt vmcnt(2)
	v_cndmask_b32_e64 v6, 0, 1, s[36:37]
	v_cmp_ne_u32_e64 s[38:39], 1, v6
	s_andn2_b64 vcc, exec, s[36:37]
	s_cbranch_vccnz .LBB0_526
	global_load_dwordx4 v[188:191], v0, s[34:35] offset:1024
	s_add_u32 s54, s34, 0x30000
	s_addc_u32 s55, s35, 0
	global_load_dwordx4 v[192:195], v0, s[54:55] offset:1024
	s_add_u32 s56, s34, 0x60000
	s_addc_u32 s57, s35, 0
	global_load_dwordx4 v[196:199], v0, s[56:57] offset:1024
	s_add_u32 s62, s34, 0x90000
	s_addc_u32 s63, s35, 0
	global_load_dwordx4 v[200:203], v0, s[62:63] offset:1024
	global_load_dwordx4 v[6:9], v0, s[30:31] offset:1024
	s_waitcnt vmcnt(0)
	v_pk_add_f32 v[10:11], v[188:189], v[192:193]
	v_pk_add_f32 v[10:11], v[10:11], v[196:197]
	v_pk_add_f32 v[12:13], v[190:191], v[194:195]
	v_pk_add_f32 v[12:13], v[12:13], v[198:199]
	v_pk_add_f32 v[54:55], v[188:189], v[192:193]
	v_pk_add_f32 v[54:55], v[54:55], v[196:197]
	v_pk_add_f32 v[54:55], v[54:55], v[200:201]
	v_pk_add_f32 v[56:57], v[190:191], v[194:195]
	v_pk_add_f32 v[56:57], v[56:57], v[198:199]
	v_pk_add_f32 v[56:57], v[56:57], v[202:203]
.LBB0_526:
	s_and_b64 vcc, exec, s[38:39]
	s_cbranch_vccnz .LBB0_528
	global_load_dwordx4 v[188:191], v0, s[34:35] offset:2048
	s_add_u32 s54, s34, 0x30000
	s_addc_u32 s55, s35, 0
	global_load_dwordx4 v[192:195], v0, s[54:55] offset:2048
	s_add_u32 s56, s34, 0x60000
	s_addc_u32 s57, s35, 0
	global_load_dwordx4 v[196:199], v0, s[56:57] offset:2048
	s_add_u32 s62, s34, 0x90000
	s_addc_u32 s63, s35, 0
	global_load_dwordx4 v[200:203], v0, s[62:63] offset:2048
	global_load_dwordx4 v[10:13], v0, s[30:31] offset:2048
	s_waitcnt vmcnt(0)
	v_pk_add_f32 v[14:15], v[188:189], v[192:193]
	v_pk_add_f32 v[14:15], v[14:15], v[196:197]
	v_pk_add_f32 v[16:17], v[190:191], v[194:195]
	v_pk_add_f32 v[16:17], v[16:17], v[198:199]
	v_pk_add_f32 v[58:59], v[188:189], v[192:193]
	v_pk_add_f32 v[58:59], v[58:59], v[196:197]
	v_pk_add_f32 v[58:59], v[58:59], v[200:201]
	v_pk_add_f32 v[60:61], v[190:191], v[194:195]
	v_pk_add_f32 v[60:61], v[60:61], v[198:199]
	v_pk_add_f32 v[60:61], v[60:61], v[202:203]
.LBB0_528:
	s_and_b64 vcc, exec, s[38:39]
	s_cbranch_vccnz .LBB0_530
	global_load_dwordx4 v[188:191], v0, s[34:35] offset:3072
	s_add_u32 s54, s34, 0x30000
	s_addc_u32 s55, s35, 0
	global_load_dwordx4 v[192:195], v0, s[54:55] offset:3072
	s_add_u32 s56, s34, 0x60000
	s_addc_u32 s57, s35, 0
	global_load_dwordx4 v[196:199], v0, s[56:57] offset:3072
	s_add_u32 s62, s34, 0x90000
	s_addc_u32 s63, s35, 0
	global_load_dwordx4 v[200:203], v0, s[62:63] offset:3072
	global_load_dwordx4 v[14:17], v0, s[30:31] offset:3072
	s_waitcnt vmcnt(0)
	v_pk_add_f32 v[20:21], v[188:189], v[192:193]
	v_pk_add_f32 v[20:21], v[20:21], v[196:197]
	v_pk_add_f32 v[22:23], v[190:191], v[194:195]
	v_pk_add_f32 v[22:23], v[22:23], v[198:199]
	v_pk_add_f32 v[62:63], v[188:189], v[192:193]
	v_pk_add_f32 v[62:63], v[62:63], v[196:197]
	v_pk_add_f32 v[62:63], v[62:63], v[200:201]
	v_pk_add_f32 v[64:65], v[190:191], v[194:195]
	v_pk_add_f32 v[64:65], v[64:65], v[198:199]
	v_pk_add_f32 v[64:65], v[64:65], v[202:203]

.Lpj_glr:
	s_load_dwordx2 s[18:19], s[0:1], 0x100
	s_lshl_b32 s26, s35, 6
	v_lshlrev_b32_e32 v179, 1, v228
	v_lshl_add_u32 v179, v227, 6, v179
	s_waitcnt vmcnt(0) lgkmcnt(0)
	s_cmp_eq_u32 s43, 0
	s_cbranch_scc0 .Lpj_epi_end
	s_add_u32 s6, s18, s26
	s_addc_u32 s7, s19, 0
	s_mov_b32 exec_lo, -1
	s_mov_b32 exec_hi, 0
	global_store_dwordx4 v179, v[2:5], s[6:7]
	global_store_dwordx4 v179, v[6:9], s[6:7] offset:16
	s_add_u32 s6, s6, 0x400
	s_addc_u32 s7, s7, 0
	global_store_dwordx4 v179, v[18:21], s[6:7]
	global_store_dwordx4 v179, v[22:25], s[6:7] offset:16
	s_add_u32 s6, s6, 0x400
	s_addc_u32 s7, s7, 0
	global_store_dwordx4 v179, v[34:37], s[6:7]
	global_store_dwordx4 v179, v[38:41], s[6:7] offset:16
	s_add_u32 s6, s6, 0x400
	s_addc_u32 s7, s7, 0
	global_store_dwordx4 v179, v[50:53], s[6:7]
	global_store_dwordx4 v179, v[54:57], s[6:7] offset:16
	s_add_u32 s6, s6, 0x400
	s_addc_u32 s7, s7, 0
	global_store_dwordx4 v179, v[66:69], s[6:7]
	global_store_dwordx4 v179, v[70:73], s[6:7] offset:16
	s_add_u32 s6, s6, 0x400
	s_addc_u32 s7, s7, 0
	global_store_dwordx4 v179, v[82:85], s[6:7]
	global_store_dwordx4 v179, v[86:89], s[6:7] offset:16
	s_add_u32 s6, s6, 0x400
	s_addc_u32 s7, s7, 0
	global_store_dwordx4 v179, v[98:101], s[6:7]
	global_store_dwordx4 v179, v[102:105], s[6:7] offset:16
	s_add_u32 s6, s6, 0x400
	s_addc_u32 s7, s7, 0
	global_store_dwordx4 v179, v[114:117], s[6:7]
	global_store_dwordx4 v179, v[118:121], s[6:7] offset:16
